# FFT twiddle-table fill unrolled (8 loads in flight) on top of fourier_out load pipelining
# speedup vs baseline: 1.0090x; 1.0028x over previous
.LBB0_297:
	global_load_dwordx2 v[6:7], v[2:3], off
	v_lshl_add_u64 v[2:3], v[2:3], 0, s[38:39]
	global_load_dwordx2 v[8:9], v[2:3], off
	v_lshl_add_u64 v[2:3], v[2:3], 0, s[38:39]
	global_load_dwordx2 v[10:11], v[2:3], off
	v_lshl_add_u64 v[2:3], v[2:3], 0, s[38:39]
	global_load_dwordx2 v[12:13], v[2:3], off
	v_lshl_add_u64 v[2:3], v[2:3], 0, s[38:39]
	global_load_dwordx2 v[14:15], v[2:3], off
	v_lshl_add_u64 v[2:3], v[2:3], 0, s[38:39]
	global_load_dwordx2 v[16:17], v[2:3], off
	v_lshl_add_u64 v[2:3], v[2:3], 0, s[38:39]
	global_load_dwordx2 v[18:19], v[2:3], off
	v_lshl_add_u64 v[2:3], v[2:3], 0, s[38:39]
	global_load_dwordx2 v[20:21], v[2:3], off
	s_waitcnt vmcnt(7)
	ds_write_b64 v5, v[6:7]
	s_waitcnt vmcnt(6)
	ds_write_b64 v5, v[8:9] offset:4096
	s_waitcnt vmcnt(5)
	ds_write_b64 v5, v[10:11] offset:8192
	s_waitcnt vmcnt(4)
	ds_write_b64 v5, v[12:13] offset:12288
	s_waitcnt vmcnt(3)
	ds_write_b64 v5, v[14:15] offset:16384
	s_waitcnt vmcnt(2)
	ds_write_b64 v5, v[16:17] offset:20480
	s_waitcnt vmcnt(1)
	ds_write_b64 v5, v[18:19] offset:24576
	s_waitcnt vmcnt(0)
	ds_write_b64 v5, v[20:21] offset:28672
